# static s_setprio 1 for waves 4-7 during the attention and RG-LRU phases
# baseline (speedup 1.0000x reference)
.LBB0_496:
	v_mul_hi_u32 v2, v6, s12
	v_lshrrev_b32_e32 v10, 8, v2
	v_mul_u32_u24_e32 v2, 0x101, v10
	v_lshl_add_u64 v[8:9], v[2:3], 2, s[4:5]
	global_load_dword v7, v[4:5], off
	v_cmp_lt_u32_e32 vcc, s13, v6
	global_load_dword v8, v[8:9], off offset:1024
	v_add_u32_e32 v9, 0x200, v6
	v_mov_b32_e32 v6, v9
	v_mul_u32_u24_e32 v9, 0x410, v10
	v_lshlrev_b32_e32 v2, 2, v2
	v_sub_u32_e32 v2, v9, v2
	v_lshl_add_u64 v[4:5], v[4:5], 0, s[8:9]
	s_or_b64 s[6:7], vcc, s[6:7]
	v_add_u32_e32 v2, v1, v2
	v_add_u32_e32 v1, 0x800, v1
	s_waitcnt vmcnt(0)
	v_sub_f32_e32 v7, v7, v8
	v_mul_f32_e32 v7, 0x3fb8aa3b, v7
	ds_write_b32 v2, v7
	s_andn2_b64 exec, exec, s[6:7]
	s_cbranch_execnz .LBB0_496
	s_or_b64 exec, exec, s[6:7]
	s_lshl_b32 s4, s65, 3
	s_add_i32 s25, s4, s70
	s_cmpk_gt_i32 s25, 0x21ff
	s_waitcnt lgkmcnt(0)
	s_barrier
	s_cbranch_scc1 .LBB0_581
	s_cmp_ge_u32 s70, 4
	s_cbranch_scc0 .Lprio_skip_a
	s_setprio 1
.Lprio_skip_a:
	s_lshl_b32 s4, s2, 8
	s_and_b32 s4, s4, 0x700
	s_add_u32 s16, s52, s4
	s_addc_u32 s17, s53, 0
	s_lshl_b32 s6, s70, 14
	s_add_i32 s63, s6, 0
	s_mov_b32 s36, 0
	v_cmp_eq_u32_e64 s[4:5], 0, v184
	s_and_b32 s62, s2, 7
	v_mov_b32_e32 v3, 0
	v_mov_b32_e32 v1, s63
	s_mov_b32 s64, 0xd900000
	s_mov_b32 s12, 0x3f803f80
	s_mov_b32 s66, 0x41000000
	s_movk_i32 s67, 0x90
	s_mov_b64 s[18:19], 0x8000
	s_mov_b64 s[20:21], 0x10000
	v_bfrev_b32_e32 v18, 1
	v_mov_b32_e32 v185, 0x100
	s_branch .LBB0_501

.LBB0_581:
	s_setprio 0
	s_cmp_lt_i32 s35, 4
	s_cbranch_scc1 .LBB0_635
	s_waitcnt vmcnt(0)
	s_barrier
	s_and_saveexec_b64 s[4:5], s[22:23]
	s_cbranch_execz .LBB0_634
	s_add_i32 s6, 0, 0x20160
	v_mov_b32_e32 v1, s6
	s_waitcnt vmcnt(0) expcnt(0) lgkmcnt(0)
	ds_read_b32 v3, v1
	s_add_i32 s6, 0, 0x20164
	v_mov_b32_e32 v1, s6
	ds_read_b32 v1, v1
	s_waitcnt lgkmcnt(1)
	v_cmp_ne_u32_e32 vcc, 0, v3
	s_cbranch_vccnz .LBB0_598
	s_load_dwordx2 s[10:11], s[86:87], 0x4
	s_add_u32 s6, s52, 0x4200
	s_addc_u32 s7, s53, 0
	s_add_u32 s8, s52, 0x4400
	s_addc_u32 s9, s53, 0
	s_waitcnt lgkmcnt(0)
	s_mul_i32 s56, s10, s33
	s_add_u32 s10, s52, 0x4500
	s_mul_i32 s56, s56, s11
	s_addc_u32 s11, s53, 0
	s_add_u32 s12, s52, 0x4600
	s_addc_u32 s13, s53, 0
	s_add_u32 s14, s52, 0x4700
	s_addc_u32 s15, s53, 0
	s_add_u32 s16, s52, 0x4800
	s_addc_u32 s17, s53, 0
	s_add_u32 s18, s52, 0x4900
	s_addc_u32 s19, s53, 0
	s_add_u32 s20, s52, 0x4a00
	s_addc_u32 s21, s53, 0
	s_add_u32 s24, s52, 0x4b00
	s_addc_u32 s25, s53, 0
	s_add_u32 s26, s52, 0x4c00
	s_addc_u32 s27, s53, 0
	s_add_u32 s28, s52, 0x4d00
	s_addc_u32 s29, s53, 0
	s_add_u32 s30, s52, 0x4e00
	s_addc_u32 s31, s53, 0
	s_add_u32 s36, s52, 0x4f00
	s_addc_u32 s37, s53, 0
	s_add_u32 s38, s52, 0x5000
	s_addc_u32 s39, s53, 0
	s_add_u32 s40, s52, 0x5100
	s_addc_u32 s41, s53, 0
	s_add_u32 s42, s52, 0x5200
	s_addc_u32 s43, s53, 0
	s_add_u32 s44, s52, 0x5300
	s_addc_u32 s45, s53, 0
	s_mov_b32 s57, 1
	v_mov_b32_e32 v17, 0
	s_branch .LBB0_586

.LBB0_909:
	s_cmp_lt_i32 s34, 7
	s_cselect_b64 s[4:5], -1, 0
	s_cmp_gt_i32 s35, 6
	s_cselect_b64 s[6:7], -1, 0
	s_and_b64 s[4:5], s[4:5], s[6:7]
	s_andn2_b64 vcc, exec, s[4:5]
	s_cbranch_vccnz .LBB0_995
	s_mov_b64 s[40:41], s[0:1]
	s_cmpk_gt_i32 s2, 0x2ff
	s_waitcnt vmcnt(0)
	v_mov_b32_e32 v106, v184
	s_cbranch_scc1 .LBB0_941
	s_cmp_ge_u32 s70, 4
	s_cbranch_scc0 .Lprio_skip_l
	s_setprio 1
.Lprio_skip_l:
	s_lshl_b32 s49, s70, 4
	s_cmp_lt_u32 s3, 64
	s_cselect_b64 s[4:5], -1, 0
	s_cmp_gt_u32 s3, 63
	s_cselect_b64 s[42:43], -1, 0
	s_lshl_b32 s51, s70, 9
	s_cmpk_gt_u32 s3, 0x1ff
	s_cselect_b64 s[6:7], -1, 0
	s_cmpk_gt_u32 s3, 0x1bf
	s_cselect_b64 s[8:9], -1, 0
	s_cmpk_gt_u32 s3, 0x17f
	s_cselect_b64 s[10:11], -1, 0
	s_cmpk_gt_u32 s3, 0x13f
	s_load_dwordx2 s[20:21], s[40:41], 0xc0
	s_cselect_b64 s[12:13], -1, 0
	s_cmpk_gt_u32 s3, 0xff
	s_cselect_b64 s[14:15], -1, 0
	s_cmpk_gt_u32 s3, 0xbf
	s_waitcnt lgkmcnt(0)
	s_cselect_b64 s[16:17], -1, 0
	s_cmpk_gt_u32 s3, 0x7f
	s_mul_i32 s3, s70, 0x3000
	v_ashrrev_i32_e32 v4, 4, v106
	s_cselect_b64 s[18:19], -1, 0
	s_add_i32 s3, s3, 0
	v_lshlrev_b32_e32 v2, 3, v4
	v_and_b32_e32 v108, 15, v106
	s_add_u32 s44, s20, 0x9700000
	v_ashrrev_i32_e32 v3, 31, v2
	s_addc_u32 s45, s21, 0
	v_lshlrev_b64 v[112:113], 8, v[2:3]
	v_lshlrev_b32_e32 v2, 2, v108
	v_ashrrev_i32_e32 v107, 31, v106
	s_add_u32 s46, s20, 0xd900000
	v_lshl_or_b32 v2, v4, 10, v2
	v_mov_b32_e32 v111, 0
	s_addc_u32 s47, s21, 0
	v_lshl_add_u32 v5, v108, 8, s3
	v_lshlrev_b32_e32 v6, 5, v4
	s_mov_b64 s[24:25], 0x2000
	v_add_u32_e32 v109, s3, v2
	v_lshl_add_u64 v[2:3], v[106:107], 1, s[20:21]
	s_mov_b64 s[20:21], 0xd904780
	v_lshl_add_u32 v1, v106, 2, s3
	v_lshl_add_u64 v[114:115], v[112:113], 0, s[24:25]
	v_lshl_add_u64 v[116:117], v[2:3], 0, s[20:21]
	s_mov_b32 s36, -1
	v_lshlrev_b32_e32 v110, 2, v108
	s_movk_i32 s3, 0x7fff
	s_mov_b32 s59, 0xffff0000
	s_mov_b32 s61, 0xbfb8aa3b
	s_mov_b32 s63, 0x42ce8ed0
	s_mov_b32 s72, 0xc2b17218
	s_mov_b32 s73, 0x7f800000
	s_mov_b32 s74, 0x3f2aaaab
	s_mov_b32 s48, 0x3ecc95a3
	s_mov_b32 s50, 0x3e9b6dac
	s_mov_b32 s58, 0x3f2aaada
	s_mov_b32 s60, 0x3f317218
	s_mov_b32 s62, 0xb102e308
	s_mov_b32 s75, 0x33800000
	s_mov_b32 s64, 0xc138aa3b
	s_mov_b32 s76, 0x3a98000
	v_add_u32_e32 v170, v5, v6
	s_mov_b32 s77, 0xf7afc000
	s_mov_b64 s[66:67], 0x4000
	s_mov_b32 s78, 0xea40000
	v_mov_b32_e32 v171, 0x7f800000
	v_mov_b32_e32 v172, v111
	v_mov_b32_e32 v173, v111
	v_mov_b32_e32 v174, v111
	v_mov_b32_e32 v175, v111
	v_mov_b32_e32 v176, v111
	s_mov_b32 s79, s2
	s_branch .LBB0_913

.LBB0_941:
	s_setprio 0
	s_cmp_lt_i32 s35, 8
	s_cbranch_scc1 .LBB0_995
	s_waitcnt vmcnt(0)
	s_waitcnt lgkmcnt(0)
	s_barrier
	s_and_saveexec_b64 s[4:5], s[22:23]
	s_cbranch_execz .LBB0_994
	s_add_i32 s3, 0, 0x20160
	v_mov_b32_e32 v1, s3
	s_waitcnt vmcnt(0) expcnt(0) lgkmcnt(0)
	ds_read_b32 v3, v1
	s_add_i32 s3, 0, 0x20164
	v_mov_b32_e32 v1, s3
	ds_read_b32 v1, v1
	s_waitcnt lgkmcnt(1)
	v_cmp_ne_u32_e32 vcc, 0, v3
	s_cbranch_vccnz .LBB0_958
	s_load_dwordx2 s[10:11], s[86:87], 0x4
	s_add_u32 s6, s52, 0x4200
	s_addc_u32 s7, s53, 0
	s_add_u32 s8, s52, 0x4400
	s_addc_u32 s9, s53, 0
	s_waitcnt lgkmcnt(0)
	s_mul_i32 s3, s10, s33
	s_add_u32 s10, s52, 0x4500
	s_mul_i32 s3, s3, s11
	s_addc_u32 s11, s53, 0
	s_add_u32 s12, s52, 0x4600
	s_addc_u32 s13, s53, 0
	s_add_u32 s14, s52, 0x4700
	s_addc_u32 s15, s53, 0
	s_add_u32 s16, s52, 0x4800
	s_addc_u32 s17, s53, 0
	s_add_u32 s18, s52, 0x4900
	s_addc_u32 s19, s53, 0
	s_add_u32 s20, s52, 0x4a00
	s_addc_u32 s21, s53, 0
	s_add_u32 s24, s52, 0x4b00
	s_addc_u32 s25, s53, 0
	s_add_u32 s26, s52, 0x4c00
	s_addc_u32 s27, s53, 0
	s_add_u32 s28, s52, 0x4d00
	s_addc_u32 s29, s53, 0
	s_add_u32 s30, s52, 0x4e00
	s_addc_u32 s31, s53, 0
	s_add_u32 s36, s52, 0x4f00
	s_addc_u32 s37, s53, 0
	s_add_u32 s38, s52, 0x5000
	s_addc_u32 s39, s53, 0
	s_add_u32 s40, s52, 0x5100
	s_addc_u32 s41, s53, 0
	s_add_u32 s42, s52, 0x5200
	s_addc_u32 s43, s53, 0
	s_add_u32 s44, s52, 0x5300
	s_addc_u32 s45, s53, 0
	s_mov_b32 s56, 1
	v_mov_b32_e32 v17, 0
	s_branch .LBB0_946
